# grid barriers B1,B2,B3,B6: XCC leader bumps one top counter that every workgroup polls (no TOPGEN/XGEN hops)
# speedup vs baseline: 1.1285x; 1.0075x over previous
; __device__ __forceinline__ unsigned xb_ld(unsigned* p)              { return __hip_atomic_load(p, __ATOMIC_RELAXED, __HIP_MEMORY_SCOPE_AGENT); }
; __device__ __forceinline__ unsigned xb_add(unsigned* p, unsigned v) { return __hip_atomic_fetch_add(p, v, __ATOMIC_RELAXED, __HIP_MEMORY_SCOPE_AGENT); }
; #define XB_SPIN(cond, bar) do { unsigned _sp = 0; while (cond) { __builtin_amdgcn_s_sleep(1); \
;     if ((++_sp & 255u) == 0u) { if (xb_ld(&(bar)[XB_TMO])) break; if (_sp > XB_SPIN_CAP) { atomicAdd(&(bar)[XB_TMO], 1u); break; } } } } while (0)
; __device__ __forceinline__ void xcd_barrier(const XcdBarrier& b) {
;     asm volatile("s_waitcnt vmcnt(0)" ::: "memory");
;     __syncthreads();
;     if (threadIdx.x == 0) {
;         unsigned* bar = b.bar;
;         __builtin_amdgcn_s_waitcnt(0);
;         unsigned nloc = b.st[0], nx = b.st[1];
;         if (nloc == 0u) { xcd_barrier_complete(bar, b.x, nloc, nx); b.st[0] = nloc; b.st[1] = nx; }
;         const unsigned old = xb_add(&bar[XB_XSUB(b.x)], 1u);
;         const unsigned gen = old / nloc;
;         if (old + 1u == (gen + 1u) * nloc) {
;             __builtin_amdgcn_fence(__ATOMIC_RELEASE, "agent");
;             asm volatile("s_waitcnt vmcnt(0)" ::: "memory");
;             const unsigned og = xb_add(&bar[XB_TOP], 1u);
;             const unsigned tg = og / nx;
;             if (og + 1u == (tg + 1u) * nx) xb_add(&bar[XB_TOPGEN], 1u);
;             else XB_SPIN(xb_ld(&bar[XB_TOPGEN]) == tg, bar);
;             __builtin_amdgcn_fence(__ATOMIC_ACQUIRE, "agent");
;             xb_add(&bar[XB_XGEN(b.x)], 1u);
.LBB0_136:
	v_readlane_b32 s0, v254, 51
	s_add_i32 s0, s0, 2
	s_cmp_ge_i32 s0, s57
	s_cbranch_scc1 .LBB0_190
	s_waitcnt vmcnt(0)
	s_waitcnt vmcnt(0) lgkmcnt(0)
	s_barrier
	s_mov_b64 s[4:5], exec
	v_readlane_b32 s2, v252, 11
	v_readlane_b32 s3, v252, 12
	s_and_b64 s[2:3], s[4:5], s[2:3]
	s_mov_b64 exec, s[2:3]
	s_cbranch_execz .Lgb1_done
	v_mov_b32_e32 v2, 0x22160
	v_mov_b32_e32 v3, 1
	ds_read2_b32 v[4:5], v2 offset1:1
	ds_add_rtn_u32 v6, v2, v3 offset:8
	v_readlane_b32 s10, v253, 52
	v_readlane_b32 s11, v253, 53
	s_add_u32 s10, s10, 0xc000
	s_addc_u32 s11, s11, 0
	s_getreg_b32 s9, hwreg(HW_REG_XCC_ID, 0, 4)
	s_lshl_b32 s9, s9, 8
	s_add_u32 s12, s10, s9
	s_addc_u32 s13, s11, 0
	v_mov_b32_e32 v2, 0
	global_atomic_add v7, v2, v3, s[12:13] offset:1024 sc0
	s_waitcnt lgkmcnt(0)
	v_readfirstlane_b32 s14, v4
	v_readfirstlane_b32 s15, v5
	v_readfirstlane_b32 s8, v6
	s_add_u32 s8, s8, 1
	s_mul_i32 s14, s14, s8
	s_mul_i32 s15, s15, s8
	s_waitcnt vmcnt(0)
	v_readfirstlane_b32 s9, v7
	s_add_u32 s9, s9, 1
	s_cmp_lg_u32 s9, s14
	s_cbranch_scc1 .Lgb1_nonleader
	buffer_wbl2 sc1
	s_waitcnt vmcnt(0)
	buffer_inv sc1
	global_atomic_add v2, v3, s[10:11]
	s_branch .Lgb1_poll

; __device__ __forceinline__ unsigned xb_ld(unsigned* p)              { return __hip_atomic_load(p, __ATOMIC_RELAXED, __HIP_MEMORY_SCOPE_AGENT); }
; __device__ __forceinline__ unsigned xb_add(unsigned* p, unsigned v) { return __hip_atomic_fetch_add(p, v, __ATOMIC_RELAXED, __HIP_MEMORY_SCOPE_AGENT); }
; #define XB_SPIN(cond, bar) do { unsigned _sp = 0; while (cond) { __builtin_amdgcn_s_sleep(1); \
;     if ((++_sp & 255u) == 0u) { if (xb_ld(&(bar)[XB_TMO])) break; if (_sp > XB_SPIN_CAP) { atomicAdd(&(bar)[XB_TMO], 1u); break; } } } } while (0)
; __device__ __forceinline__ void xcd_barrier(const XcdBarrier& b) {
;     ...
;             else XB_SPIN(xb_ld(&bar[XB_TOPGEN]) == tg, bar);
;             __builtin_amdgcn_fence(__ATOMIC_ACQUIRE, "agent");
;             xb_add(&bar[XB_XGEN(b.x)], 1u);
;             asm volatile("s_waitcnt vmcnt(0)" ::: "memory");
;         } else {
;             XB_SPIN(xb_ld(&bar[XB_XGEN(b.x)]) == gen, bar);
;             __builtin_amdgcn_fence(__ATOMIC_ACQUIRE, "agent");
;             asm volatile("s_waitcnt vmcnt(0)" ::: "memory");
;         }
.Lgb1_poll:
	s_mov_b32 s8, 0
.Lgb1_spin:
	global_load_dword v4, v2, s[10:11] sc1
	s_waitcnt vmcnt(0)
	v_readfirstlane_b32 s9, v4
	s_cmp_ge_u32 s9, s15
	s_cbranch_scc1 .Lgb1_done
	s_sleep 1
	s_add_u32 s8, s8, 1
	s_cmp_lt_u32 s8, 0x40000
	s_cbranch_scc1 .Lgb1_spin
.Lgb1_done:
	s_or_b64 exec, exec, s[4:5]
	s_waitcnt vmcnt(0) lgkmcnt(0)
	s_barrier

; __device__ __forceinline__ unsigned xb_ld(unsigned* p)              { return __hip_atomic_load(p, __ATOMIC_RELAXED, __HIP_MEMORY_SCOPE_AGENT); }
; __device__ __forceinline__ unsigned xb_add(unsigned* p, unsigned v) { return __hip_atomic_fetch_add(p, v, __ATOMIC_RELAXED, __HIP_MEMORY_SCOPE_AGENT); }
; #define XB_SPIN(cond, bar) do { unsigned _sp = 0; while (cond) { __builtin_amdgcn_s_sleep(1); \
;     if ((++_sp & 255u) == 0u) { if (xb_ld(&(bar)[XB_TMO])) break; if (_sp > XB_SPIN_CAP) { atomicAdd(&(bar)[XB_TMO], 1u); break; } } } } while (0)
; __device__ __forceinline__ void xcd_barrier(const XcdBarrier& b) {
;     asm volatile("s_waitcnt vmcnt(0)" ::: "memory");
;     __syncthreads();
;     if (threadIdx.x == 0) {
;         unsigned* bar = b.bar;
;         __builtin_amdgcn_s_waitcnt(0);
;         unsigned nloc = b.st[0], nx = b.st[1];
;         if (nloc == 0u) { xcd_barrier_complete(bar, b.x, nloc, nx); b.st[0] = nloc; b.st[1] = nx; }
;         const unsigned old = xb_add(&bar[XB_XSUB(b.x)], 1u);
;         const unsigned gen = old / nloc;
;         if (old + 1u == (gen + 1u) * nloc) {
;             __builtin_amdgcn_fence(__ATOMIC_RELEASE, "agent");
;             asm volatile("s_waitcnt vmcnt(0)" ::: "memory");
;             const unsigned og = xb_add(&bar[XB_TOP], 1u);
;             const unsigned tg = og / nx;
;             if (og + 1u == (tg + 1u) * nx) xb_add(&bar[XB_TOPGEN], 1u);
;             else XB_SPIN(xb_ld(&bar[XB_TOPGEN]) == tg, bar);
;             __builtin_amdgcn_fence(__ATOMIC_ACQUIRE, "agent");
;             xb_add(&bar[XB_XGEN(b.x)], 1u);
.LBB0_218:
	v_readlane_b32 s0, v254, 51
	s_add_i32 s0, s0, 4
	s_cmp_ge_i32 s0, s57
	s_mov_b64 s[8:9], 0
	s_cbranch_scc1 .LBB0_272
	s_waitcnt vmcnt(0)
	s_waitcnt vmcnt(0) lgkmcnt(0)
	s_barrier
	s_mov_b64 s[4:5], exec
	v_readlane_b32 s2, v252, 11
	v_readlane_b32 s3, v252, 12
	s_and_b64 s[2:3], s[4:5], s[2:3]
	s_mov_b64 exec, s[2:3]
	s_cbranch_execz .Lgb2_done
	v_mov_b32_e32 v2, 0x22160
	v_mov_b32_e32 v3, 1
	ds_read2_b32 v[4:5], v2 offset1:1
	ds_add_rtn_u32 v6, v2, v3 offset:8
	v_readlane_b32 s10, v253, 52
	v_readlane_b32 s11, v253, 53
	s_add_u32 s10, s10, 0xc000
	s_addc_u32 s11, s11, 0
	s_getreg_b32 s9, hwreg(HW_REG_XCC_ID, 0, 4)
	s_lshl_b32 s9, s9, 8
	s_add_u32 s12, s10, s9
	s_addc_u32 s13, s11, 0
	v_mov_b32_e32 v2, 0
	global_atomic_add v7, v2, v3, s[12:13] offset:1024 sc0
	s_waitcnt lgkmcnt(0)
	v_readfirstlane_b32 s14, v4
	v_readfirstlane_b32 s15, v5
	v_readfirstlane_b32 s8, v6
	s_add_u32 s8, s8, 1
	s_mul_i32 s14, s14, s8
	s_mul_i32 s15, s15, s8
	s_waitcnt vmcnt(0)
	v_readfirstlane_b32 s9, v7
	s_add_u32 s9, s9, 1
	s_cmp_lg_u32 s9, s14
	s_cbranch_scc1 .Lgb2_nonleader
	buffer_wbl2 sc1
	s_waitcnt vmcnt(0)
	buffer_inv sc1
	global_atomic_add v2, v3, s[10:11]
	s_branch .Lgb2_poll

; __device__ __forceinline__ unsigned xb_ld(unsigned* p)              { return __hip_atomic_load(p, __ATOMIC_RELAXED, __HIP_MEMORY_SCOPE_AGENT); }
; __device__ __forceinline__ unsigned xb_add(unsigned* p, unsigned v) { return __hip_atomic_fetch_add(p, v, __ATOMIC_RELAXED, __HIP_MEMORY_SCOPE_AGENT); }
; #define XB_SPIN(cond, bar) do { unsigned _sp = 0; while (cond) { __builtin_amdgcn_s_sleep(1); \
;     if ((++_sp & 255u) == 0u) { if (xb_ld(&(bar)[XB_TMO])) break; if (_sp > XB_SPIN_CAP) { atomicAdd(&(bar)[XB_TMO], 1u); break; } } } } while (0)
; __device__ __forceinline__ void xcd_barrier(const XcdBarrier& b) {
;     ...
;             else XB_SPIN(xb_ld(&bar[XB_TOPGEN]) == tg, bar);
;             __builtin_amdgcn_fence(__ATOMIC_ACQUIRE, "agent");
;             xb_add(&bar[XB_XGEN(b.x)], 1u);
;             asm volatile("s_waitcnt vmcnt(0)" ::: "memory");
;         } else {
;             XB_SPIN(xb_ld(&bar[XB_XGEN(b.x)]) == gen, bar);
;             __builtin_amdgcn_fence(__ATOMIC_ACQUIRE, "agent");
;             asm volatile("s_waitcnt vmcnt(0)" ::: "memory");
;         }
;     }
;     __syncthreads();
.Lgb2_done:
	s_or_b64 exec, exec, s[4:5]
	s_waitcnt vmcnt(0) lgkmcnt(0)
	s_barrier
	s_mov_b64 s[8:9], -1

; __device__ __forceinline__ unsigned xb_ld(unsigned* p)              { return __hip_atomic_load(p, __ATOMIC_RELAXED, __HIP_MEMORY_SCOPE_AGENT); }
; __device__ __forceinline__ unsigned xb_add(unsigned* p, unsigned v) { return __hip_atomic_fetch_add(p, v, __ATOMIC_RELAXED, __HIP_MEMORY_SCOPE_AGENT); }
; #define XB_SPIN(cond, bar) do { unsigned _sp = 0; while (cond) { __builtin_amdgcn_s_sleep(1); \
;     if ((++_sp & 255u) == 0u) { if (xb_ld(&(bar)[XB_TMO])) break; if (_sp > XB_SPIN_CAP) { atomicAdd(&(bar)[XB_TMO], 1u); break; } } } } while (0)
; __device__ __forceinline__ void xcd_barrier(const XcdBarrier& b) {
;     asm volatile("s_waitcnt vmcnt(0)" ::: "memory");
;     __syncthreads();
;     if (threadIdx.x == 0) {
;         unsigned* bar = b.bar;
;         __builtin_amdgcn_s_waitcnt(0);
;         unsigned nloc = b.st[0], nx = b.st[1];
;         if (nloc == 0u) { xcd_barrier_complete(bar, b.x, nloc, nx); b.st[0] = nloc; b.st[1] = nx; }
;         const unsigned old = xb_add(&bar[XB_XSUB(b.x)], 1u);
;         const unsigned gen = old / nloc;
;         if (old + 1u == (gen + 1u) * nloc) {
;             __builtin_amdgcn_fence(__ATOMIC_RELEASE, "agent");
;             asm volatile("s_waitcnt vmcnt(0)" ::: "memory");
;             const unsigned og = xb_add(&bar[XB_TOP], 1u);
;             const unsigned tg = og / nx;
;             if (og + 1u == (tg + 1u) * nx) xb_add(&bar[XB_TOPGEN], 1u);
;             else XB_SPIN(xb_ld(&bar[XB_TOPGEN]) == tg, bar);
;             __builtin_amdgcn_fence(__ATOMIC_ACQUIRE, "agent");
;             xb_add(&bar[XB_XGEN(b.x)], 1u);
.LBB0_427:
	v_readlane_b32 s0, v254, 51
	s_add_i32 s0, s0, 4
	s_cmp_ge_i32 s0, s57
	s_cbranch_scc1 .LBB0_481
	s_waitcnt vmcnt(0)
	s_waitcnt vmcnt(0) lgkmcnt(0)
	s_barrier
	s_mov_b64 s[4:5], exec
	v_readlane_b32 s2, v252, 11
	v_readlane_b32 s3, v252, 12
	s_and_b64 s[2:3], s[4:5], s[2:3]
	s_mov_b64 exec, s[2:3]
	s_cbranch_execz .Lgb3_done
	v_mov_b32_e32 v2, 0x22160
	v_mov_b32_e32 v3, 1
	ds_read2_b32 v[4:5], v2 offset1:1
	ds_add_rtn_u32 v6, v2, v3 offset:8
	v_readlane_b32 s10, v253, 52
	v_readlane_b32 s11, v253, 53
	s_add_u32 s10, s10, 0xc000
	s_addc_u32 s11, s11, 0
	s_getreg_b32 s9, hwreg(HW_REG_XCC_ID, 0, 4)
	s_lshl_b32 s9, s9, 8
	s_add_u32 s12, s10, s9
	s_addc_u32 s13, s11, 0
	v_mov_b32_e32 v2, 0
	global_atomic_add v7, v2, v3, s[12:13] offset:1024 sc0
	s_waitcnt lgkmcnt(0)
	v_readfirstlane_b32 s14, v4
	v_readfirstlane_b32 s15, v5
	v_readfirstlane_b32 s8, v6
	s_add_u32 s8, s8, 1
	s_mul_i32 s14, s14, s8
	s_mul_i32 s15, s15, s8
	s_waitcnt vmcnt(0)
	v_readfirstlane_b32 s9, v7
	s_add_u32 s9, s9, 1
	s_cmp_lg_u32 s9, s14
	s_cbranch_scc1 .Lgb3_nonleader
	buffer_wbl2 sc1
	s_waitcnt vmcnt(0)
	buffer_inv sc1
	global_atomic_add v2, v3, s[10:11]
	s_branch .Lgb3_poll

; __device__ __forceinline__ unsigned xb_ld(unsigned* p)              { return __hip_atomic_load(p, __ATOMIC_RELAXED, __HIP_MEMORY_SCOPE_AGENT); }
; __device__ __forceinline__ unsigned xb_add(unsigned* p, unsigned v) { return __hip_atomic_fetch_add(p, v, __ATOMIC_RELAXED, __HIP_MEMORY_SCOPE_AGENT); }
; #define XB_SPIN(cond, bar) do { unsigned _sp = 0; while (cond) { __builtin_amdgcn_s_sleep(1); \
;     if ((++_sp & 255u) == 0u) { if (xb_ld(&(bar)[XB_TMO])) break; if (_sp > XB_SPIN_CAP) { atomicAdd(&(bar)[XB_TMO], 1u); break; } } } } while (0)
; __device__ __forceinline__ void xcd_barrier(const XcdBarrier& b) {
;     asm volatile("s_waitcnt vmcnt(0)" ::: "memory");
;     __syncthreads();
;     if (threadIdx.x == 0) {
;         unsigned* bar = b.bar;
;         __builtin_amdgcn_s_waitcnt(0);
;         unsigned nloc = b.st[0], nx = b.st[1];
;         if (nloc == 0u) { xcd_barrier_complete(bar, b.x, nloc, nx); b.st[0] = nloc; b.st[1] = nx; }
;         const unsigned old = xb_add(&bar[XB_XSUB(b.x)], 1u);
;         const unsigned gen = old / nloc;
;         if (old + 1u == (gen + 1u) * nloc) {
;             __builtin_amdgcn_fence(__ATOMIC_RELEASE, "agent");
;             asm volatile("s_waitcnt vmcnt(0)" ::: "memory");
;             const unsigned og = xb_add(&bar[XB_TOP], 1u);
;             const unsigned tg = og / nx;
;             if (og + 1u == (tg + 1u) * nx) xb_add(&bar[XB_TOPGEN], 1u);
;             else XB_SPIN(xb_ld(&bar[XB_TOPGEN]) == tg, bar);
;             __builtin_amdgcn_fence(__ATOMIC_ACQUIRE, "agent");
;             xb_add(&bar[XB_XGEN(b.x)], 1u);
.LBB0_775:
	v_readlane_b32 s0, v254, 51
	s_add_i32 s0, s0, 7
	s_cmp_ge_i32 s0, s57
	s_cbranch_scc1 .LBB0_108
	v_readlane_b32 s2, v254, 52
	s_cmp_eq_u32 s2, 3
	s_cbranch_scc1 .Llb6_entry
	s_waitcnt vmcnt(0)
	s_waitcnt vmcnt(0) lgkmcnt(0)
	s_barrier
	s_mov_b64 s[4:5], exec
	v_readlane_b32 s2, v252, 11
	v_readlane_b32 s3, v252, 12
	s_and_b64 s[2:3], s[4:5], s[2:3]
	s_mov_b64 exec, s[2:3]
	s_cbranch_execz .Lgb6_done
	v_mov_b32_e32 v2, 0x22160
	v_mov_b32_e32 v3, 1
	ds_read2_b32 v[4:5], v2 offset1:1
	ds_add_rtn_u32 v6, v2, v3 offset:8
	v_readlane_b32 s10, v253, 52
	v_readlane_b32 s11, v253, 53
	s_add_u32 s10, s10, 0xc000
	s_addc_u32 s11, s11, 0
	s_getreg_b32 s9, hwreg(HW_REG_XCC_ID, 0, 4)
	s_lshl_b32 s9, s9, 8
	s_add_u32 s12, s10, s9
	s_addc_u32 s13, s11, 0
	v_mov_b32_e32 v2, 0
	global_atomic_add v7, v2, v3, s[12:13] offset:1024 sc0
	s_waitcnt lgkmcnt(0)
	v_readfirstlane_b32 s14, v4
	v_readfirstlane_b32 s15, v5
	v_readfirstlane_b32 s8, v6
	s_add_u32 s8, s8, 1
	s_mul_i32 s14, s14, s8
	s_mul_i32 s15, s15, s8
	s_waitcnt vmcnt(0)
	v_readfirstlane_b32 s9, v7
	s_add_u32 s9, s9, 1
	s_cmp_lg_u32 s9, s14
	s_cbranch_scc1 .Lgb6_nonleader
	buffer_wbl2 sc1
	s_waitcnt vmcnt(0)
	buffer_inv sc1
	global_atomic_add v2, v3, s[10:11]
	s_branch .Lgb6_poll

; __device__ __forceinline__ unsigned xb_ld(unsigned* p)              { return __hip_atomic_load(p, __ATOMIC_RELAXED, __HIP_MEMORY_SCOPE_AGENT); }
; #define XB_SPIN(cond, bar) do { unsigned _sp = 0; while (cond) { __builtin_amdgcn_s_sleep(1); \
;     if ((++_sp & 255u) == 0u) { if (xb_ld(&(bar)[XB_TMO])) break; if (_sp > XB_SPIN_CAP) { atomicAdd(&(bar)[XB_TMO], 1u); break; } } } } while (0)
; __device__ __forceinline__ void xcd_barrier(const XcdBarrier& b) {
;     ...
;             XB_SPIN(xb_ld(&bar[XB_XGEN(b.x)]) == gen, bar);
;             __builtin_amdgcn_fence(__ATOMIC_ACQUIRE, "agent");
;             asm volatile("s_waitcnt vmcnt(0)" ::: "memory");
;         }
;     }
;     __syncthreads();
.Lgb6_done:
	s_or_b64 exec, exec, s[4:5]
	s_waitcnt vmcnt(0) lgkmcnt(0)
	s_barrier
	s_branch .LBB0_108
